# GEMM2 epilogue residual loads: four consecutive lanes fetch one 64-byte row segment, ds_bpermute lane transpose back to the accumulator layout replaces the register copies
# speedup vs baseline: 1.0018x; 1.0018x over previous
.LBB0_935:
	s_add_u32 s2, s12, 0xfffc0080
	s_addc_u32 s3, s13, -1
	s_add_i32 s38, 32, 0x10000
	v_add_u32_e32 v152, s38, v145
	ds_read_b128 v[140:143], v152
	ds_read_b128 v[148:151], v152 offset:1024
	ds_read_b128 v[164:167], v152 offset:2048
	ds_read_b128 v[168:171], v152 offset:3072
	s_cmp_eq_u32 vcc_hi, 12
	s_cselect_b32 s3, s31, s3
	s_cselect_b32 s2, s4, s2
	s_cselect_b32 s19, s11, s35
	s_cselect_b32 s18, vcc_lo, s34
	s_add_i32 m0, s14, 0xc000
	ds_read_b128 v[172:175], v147
	ds_read_b128 v[176:179], v147 offset:1024
	ds_read_b128 v[182:185], v147 offset:2048
	ds_read_b128 v[186:189], v147 offset:3072
	ds_read_b128 v[190:193], v147 offset:4096
	ds_read_b128 v[194:197], v147 offset:5120
	ds_read_b128 v[198:201], v147 offset:6144
	ds_read_b128 v[202:205], v147 offset:7168
	global_load_lds_dwordx4 v136, s[12:13]
	s_add_i32 m0, s14, 0xe000
	s_nop 0
	global_load_lds_dwordx4 v138, s[12:13]
	s_waitcnt lgkmcnt(8)
	s_barrier
	s_waitcnt lgkmcnt(0)
	s_waitcnt lgkmcnt(0)
	v_mfma_f32_16x16x32_bf16 v[126:129], v[140:143], v[172:175], v[126:129]
	v_mfma_f32_16x16x32_bf16 v[122:125], v[164:167], v[172:175], v[122:125]
	v_mfma_f32_16x16x32_bf16 v[110:113], v[140:143], v[182:185], v[110:113]
	v_mfma_f32_16x16x32_bf16 v[106:109], v[164:167], v[182:185], v[106:109]
	v_mfma_f32_16x16x32_bf16 v[94:97], v[140:143], v[190:193], v[94:97]
	v_mfma_f32_16x16x32_bf16 v[90:93], v[164:167], v[190:193], v[90:93]
	v_mfma_f32_16x16x32_bf16 v[78:81], v[140:143], v[198:201], v[78:81]
	v_mfma_f32_16x16x32_bf16 v[74:77], v[164:167], v[198:201], v[74:77]
	v_mfma_f32_16x16x32_bf16 v[126:129], v[148:151], v[176:179], v[126:129]
	v_mfma_f32_16x16x32_bf16 v[122:125], v[168:171], v[176:179], v[122:125]
	v_mfma_f32_16x16x32_bf16 v[110:113], v[148:151], v[186:189], v[110:113]
	v_mfma_f32_16x16x32_bf16 v[106:109], v[168:171], v[186:189], v[106:109]
	v_mfma_f32_16x16x32_bf16 v[94:97], v[148:151], v[194:197], v[94:97]
	v_mfma_f32_16x16x32_bf16 v[90:93], v[168:171], v[194:197], v[90:93]
	v_mfma_f32_16x16x32_bf16 v[78:81], v[148:151], v[202:205], v[78:81]
	v_mfma_f32_16x16x32_bf16 v[74:77], v[168:171], v[202:205], v[74:77]
	s_barrier
	s_add_i32 s24, 32, 0x14000
	s_add_i32 s38, s38, s7
	ds_read_b128 v[206:209], v152 offset:16384
	ds_read_b128 v[210:213], v152 offset:17408
	ds_read_b128 v[214:217], v152 offset:18432
	ds_read_b128 v[218:221], v152 offset:19456
	s_mov_b32 m0, s38
	s_nop 0
	global_load_lds_dwordx4 v154, s[18:19]
	s_add_i32 m0, s38, 0x2000
	s_nop 0
	global_load_lds_dwordx4 v130, s[18:19]
	s_barrier
	s_waitcnt lgkmcnt(0)
	s_waitcnt lgkmcnt(0)
	v_mfma_f32_16x16x32_bf16 v[118:121], v[206:209], v[172:175], v[118:121]
	v_mfma_f32_16x16x32_bf16 v[114:117], v[214:217], v[172:175], v[114:117]
	v_mfma_f32_16x16x32_bf16 v[102:105], v[206:209], v[182:185], v[102:105]
	v_mfma_f32_16x16x32_bf16 v[98:101], v[214:217], v[182:185], v[98:101]
	v_mfma_f32_16x16x32_bf16 v[86:89], v[206:209], v[190:193], v[86:89]
	v_mfma_f32_16x16x32_bf16 v[82:85], v[214:217], v[190:193], v[82:85]
	v_mfma_f32_16x16x32_bf16 v[70:73], v[206:209], v[198:201], v[70:73]
	v_mfma_f32_16x16x32_bf16 v[66:69], v[214:217], v[198:201], v[66:69]
	v_mfma_f32_16x16x32_bf16 v[118:121], v[210:213], v[176:179], v[118:121]
	v_mfma_f32_16x16x32_bf16 v[114:117], v[218:221], v[176:179], v[114:117]
	v_mfma_f32_16x16x32_bf16 v[102:105], v[210:213], v[186:189], v[102:105]
	v_mfma_f32_16x16x32_bf16 v[98:101], v[218:221], v[186:189], v[98:101]
	v_mfma_f32_16x16x32_bf16 v[86:89], v[210:213], v[194:197], v[86:89]
	v_mfma_f32_16x16x32_bf16 v[82:85], v[218:221], v[194:197], v[82:85]
	v_mfma_f32_16x16x32_bf16 v[70:73], v[210:213], v[202:205], v[70:73]
	v_mfma_f32_16x16x32_bf16 v[66:69], v[218:221], v[202:205], v[66:69]
	s_mov_b32 m0, s14
	s_mov_b64 s[98:99], s[2:3]
	s_barrier
	ds_read_b128 v[172:175], v147 offset:16384
	ds_read_b128 v[176:179], v147 offset:17408
	ds_read_b128 v[182:185], v147 offset:18432
	ds_read_b128 v[186:189], v147 offset:19456
	ds_read_b128 v[190:193], v147 offset:20480
	ds_read_b128 v[194:197], v147 offset:21504
	ds_read_b128 v[198:201], v147 offset:22528
	ds_read_b128 v[202:205], v147 offset:23552
	global_load_lds_dwordx4 v134, s[2:3]
	s_mov_b32 m0, s20
	s_nop 0
	global_load_lds_dwordx4 v132, s[2:3]
	s_barrier
	s_waitcnt lgkmcnt(0)
	s_waitcnt lgkmcnt(0)
	v_mfma_f32_16x16x32_bf16 v[62:65], v[140:143], v[172:175], v[62:65]
	v_mfma_f32_16x16x32_bf16 v[58:61], v[164:167], v[172:175], v[58:61]
	v_mfma_f32_16x16x32_bf16 v[46:49], v[140:143], v[182:185], v[46:49]
	v_mfma_f32_16x16x32_bf16 v[42:45], v[164:167], v[182:185], v[42:45]
	v_mfma_f32_16x16x32_bf16 v[30:33], v[140:143], v[190:193], v[30:33]
	v_mfma_f32_16x16x32_bf16 v[26:29], v[164:167], v[190:193], v[26:29]
	v_mfma_f32_16x16x32_bf16 v[14:17], v[140:143], v[198:201], v[14:17]
	v_mfma_f32_16x16x32_bf16 v[10:13], v[164:167], v[198:201], v[10:13]
	v_mfma_f32_16x16x32_bf16 v[62:65], v[148:151], v[176:179], v[62:65]
	v_mfma_f32_16x16x32_bf16 v[58:61], v[168:171], v[176:179], v[58:61]
	v_mfma_f32_16x16x32_bf16 v[46:49], v[148:151], v[186:189], v[46:49]
	v_mfma_f32_16x16x32_bf16 v[42:45], v[168:171], v[186:189], v[42:45]
	v_mfma_f32_16x16x32_bf16 v[30:33], v[148:151], v[194:197], v[30:33]
	v_mfma_f32_16x16x32_bf16 v[26:29], v[168:171], v[194:197], v[26:29]
	v_mfma_f32_16x16x32_bf16 v[14:17], v[148:151], v[202:205], v[14:17]
	v_mfma_f32_16x16x32_bf16 v[10:13], v[168:171], v[202:205], v[10:13]
	s_barrier
	s_add_u32 s38, s18, 0x40000
	s_addc_u32 s39, s19, 0
	s_add_i32 s24, s24, s7
	s_mov_b32 m0, s24
	s_nop 0
	global_load_lds_dwordx4 v154, s[38:39]
	s_add_i32 m0, s24, 0x2000
	s_nop 0
	global_load_lds_dwordx4 v130, s[38:39]
	s_waitcnt vmcnt(6)
	s_barrier
	v_mfma_f32_16x16x32_bf16 v[54:57], v[206:209], v[172:175], v[54:57]
	v_mfma_f32_16x16x32_bf16 v[50:53], v[214:217], v[172:175], v[50:53]
	v_mfma_f32_16x16x32_bf16 v[38:41], v[206:209], v[182:185], v[38:41]
	v_mfma_f32_16x16x32_bf16 v[34:37], v[214:217], v[182:185], v[34:37]
	v_mfma_f32_16x16x32_bf16 v[22:25], v[206:209], v[190:193], v[22:25]
	v_mfma_f32_16x16x32_bf16 v[18:21], v[214:217], v[190:193], v[18:21]
	v_mfma_f32_16x16x32_bf16 v[6:9], v[206:209], v[198:201], v[6:9]
	v_mfma_f32_16x16x32_bf16 v[2:5], v[214:217], v[198:201], v[2:5]
	v_mfma_f32_16x16x32_bf16 v[54:57], v[210:213], v[176:179], v[54:57]
	v_mfma_f32_16x16x32_bf16 v[50:53], v[218:221], v[176:179], v[50:53]
	v_mfma_f32_16x16x32_bf16 v[38:41], v[210:213], v[186:189], v[38:41]
	v_mfma_f32_16x16x32_bf16 v[34:37], v[218:221], v[186:189], v[34:37]
	v_mfma_f32_16x16x32_bf16 v[22:25], v[210:213], v[194:197], v[22:25]
	v_mfma_f32_16x16x32_bf16 v[18:21], v[218:221], v[194:197], v[18:21]
	v_mfma_f32_16x16x32_bf16 v[6:9], v[210:213], v[202:205], v[6:9]
	v_mfma_f32_16x16x32_bf16 v[2:5], v[218:221], v[202:205], v[2:5]
	s_add_i32 s24, 32, 0x18000
	s_barrier
	ds_read_b128 v[140:143], v152 offset:32768
	ds_read_b128 v[148:151], v152 offset:33792
	ds_read_b128 v[164:167], v152 offset:34816
	ds_read_b128 v[168:171], v152 offset:35840
	s_add_u32 s2, s2, 0x40000
	s_addc_u32 s3, s3, 0
	s_mov_b32 m0, s21
	ds_read_b128 v[172:175], v147 offset:32768
	ds_read_b128 v[176:179], v147 offset:33792
	ds_read_b128 v[182:185], v147 offset:34816
	ds_read_b128 v[186:189], v147 offset:35840
	ds_read_b128 v[190:193], v147 offset:36864
	ds_read_b128 v[194:197], v147 offset:37888
	ds_read_b128 v[198:201], v147 offset:38912
	ds_read_b128 v[202:205], v147 offset:39936
	global_load_lds_dwordx4 v134, s[2:3]
	s_mov_b32 m0, s22
	s_nop 0
	global_load_lds_dwordx4 v132, s[2:3]
	s_waitcnt lgkmcnt(8)
	s_barrier
	s_waitcnt lgkmcnt(0)
	s_waitcnt lgkmcnt(0)
	v_mfma_f32_16x16x32_bf16 v[126:129], v[140:143], v[172:175], v[126:129]
	v_mfma_f32_16x16x32_bf16 v[122:125], v[164:167], v[172:175], v[122:125]
	v_mfma_f32_16x16x32_bf16 v[110:113], v[140:143], v[182:185], v[110:113]
	v_mfma_f32_16x16x32_bf16 v[106:109], v[164:167], v[182:185], v[106:109]
	v_mfma_f32_16x16x32_bf16 v[94:97], v[140:143], v[190:193], v[94:97]
	v_mfma_f32_16x16x32_bf16 v[90:93], v[164:167], v[190:193], v[90:93]
	v_mfma_f32_16x16x32_bf16 v[78:81], v[140:143], v[198:201], v[78:81]
	v_mfma_f32_16x16x32_bf16 v[74:77], v[164:167], v[198:201], v[74:77]
	v_mfma_f32_16x16x32_bf16 v[126:129], v[148:151], v[176:179], v[126:129]
	v_mfma_f32_16x16x32_bf16 v[122:125], v[168:171], v[176:179], v[122:125]
	v_mfma_f32_16x16x32_bf16 v[110:113], v[148:151], v[186:189], v[110:113]
	v_mfma_f32_16x16x32_bf16 v[106:109], v[168:171], v[186:189], v[106:109]
	v_mfma_f32_16x16x32_bf16 v[94:97], v[148:151], v[194:197], v[94:97]
	v_mfma_f32_16x16x32_bf16 v[90:93], v[168:171], v[194:197], v[90:93]
	v_mfma_f32_16x16x32_bf16 v[78:81], v[148:151], v[202:205], v[78:81]
	v_mfma_f32_16x16x32_bf16 v[74:77], v[168:171], v[202:205], v[74:77]
	s_barrier
	s_add_i32 s38, 32, 0x1c000
	s_add_i32 s2, s24, s7
	s_mov_b32 m0, s2
	ds_read_b128 v[206:209], v152 offset:49152
	ds_read_b128 v[210:213], v152 offset:50176
	ds_read_b128 v[214:217], v152 offset:51200
	ds_read_b128 v[218:221], v152 offset:52224
	s_add_u32 s100, s18, 128
	s_addc_u32 s101, s19, 0
	global_load_lds_dwordx4 v154, s[100:101]
	s_add_i32 m0, s2, 0x2000
	s_nop 0
	global_load_lds_dwordx4 v130, s[100:101]
	s_barrier
	s_waitcnt lgkmcnt(0)
	s_waitcnt lgkmcnt(0)
	v_mfma_f32_16x16x32_bf16 v[118:121], v[206:209], v[172:175], v[118:121]
	v_mfma_f32_16x16x32_bf16 v[114:117], v[214:217], v[172:175], v[114:117]
	v_mfma_f32_16x16x32_bf16 v[102:105], v[206:209], v[182:185], v[102:105]
	v_mfma_f32_16x16x32_bf16 v[98:101], v[214:217], v[182:185], v[98:101]
	v_mfma_f32_16x16x32_bf16 v[86:89], v[206:209], v[190:193], v[86:89]
	v_mfma_f32_16x16x32_bf16 v[82:85], v[214:217], v[190:193], v[82:85]
	v_mfma_f32_16x16x32_bf16 v[70:73], v[206:209], v[198:201], v[70:73]
	v_mfma_f32_16x16x32_bf16 v[66:69], v[214:217], v[198:201], v[66:69]
	v_mfma_f32_16x16x32_bf16 v[118:121], v[210:213], v[176:179], v[118:121]
	v_mfma_f32_16x16x32_bf16 v[114:117], v[218:221], v[176:179], v[114:117]
	v_mfma_f32_16x16x32_bf16 v[102:105], v[210:213], v[186:189], v[102:105]
	v_mfma_f32_16x16x32_bf16 v[98:101], v[218:221], v[186:189], v[98:101]
	v_mfma_f32_16x16x32_bf16 v[86:89], v[210:213], v[194:197], v[86:89]
	v_mfma_f32_16x16x32_bf16 v[82:85], v[218:221], v[194:197], v[82:85]
	v_mfma_f32_16x16x32_bf16 v[70:73], v[210:213], v[202:205], v[70:73]
	v_mfma_f32_16x16x32_bf16 v[66:69], v[218:221], v[202:205], v[66:69]
	s_mov_b32 m0, s23
	s_barrier
	ds_read_b128 v[172:175], v147 offset:49152
	ds_read_b128 v[176:179], v147 offset:50176
	ds_read_b128 v[182:185], v147 offset:51200
	ds_read_b128 v[186:189], v147 offset:52224
	ds_read_b128 v[190:193], v147 offset:53248
	ds_read_b128 v[194:197], v147 offset:54272
	ds_read_b128 v[198:201], v147 offset:55296
	ds_read_b128 v[202:205], v147 offset:56320
	s_add_u32 s98, s98, 128
	s_addc_u32 s99, s99, 0
	global_load_lds_dwordx4 v134, s[98:99]
	s_mov_b32 m0, s28
	s_nop 0
	global_load_lds_dwordx4 v132, s[98:99]
	s_barrier
	s_waitcnt lgkmcnt(0)
	s_waitcnt lgkmcnt(0)
	v_mfma_f32_16x16x32_bf16 v[62:65], v[140:143], v[172:175], v[62:65]
	v_mfma_f32_16x16x32_bf16 v[58:61], v[164:167], v[172:175], v[58:61]
	v_mfma_f32_16x16x32_bf16 v[46:49], v[140:143], v[182:185], v[46:49]
	v_mfma_f32_16x16x32_bf16 v[42:45], v[164:167], v[182:185], v[42:45]
	v_mfma_f32_16x16x32_bf16 v[30:33], v[140:143], v[190:193], v[30:33]
	v_mfma_f32_16x16x32_bf16 v[26:29], v[164:167], v[190:193], v[26:29]
	v_mfma_f32_16x16x32_bf16 v[14:17], v[140:143], v[198:201], v[14:17]
	v_mfma_f32_16x16x32_bf16 v[10:13], v[164:167], v[198:201], v[10:13]
	v_mfma_f32_16x16x32_bf16 v[62:65], v[148:151], v[176:179], v[62:65]
	v_mfma_f32_16x16x32_bf16 v[58:61], v[168:171], v[176:179], v[58:61]
	v_mfma_f32_16x16x32_bf16 v[46:49], v[148:151], v[186:189], v[46:49]
	v_mfma_f32_16x16x32_bf16 v[42:45], v[168:171], v[186:189], v[42:45]
	v_mfma_f32_16x16x32_bf16 v[30:33], v[148:151], v[194:197], v[30:33]
	v_mfma_f32_16x16x32_bf16 v[26:29], v[168:171], v[194:197], v[26:29]
	v_mfma_f32_16x16x32_bf16 v[14:17], v[148:151], v[202:205], v[14:17]
	v_mfma_f32_16x16x32_bf16 v[10:13], v[168:171], v[202:205], v[10:13]
	s_barrier
	s_add_u32 s2, s18, 0x40080
	s_addc_u32 s3, s19, 0
	s_add_i32 s18, s38, s7
	s_mov_b32 m0, s18
	s_nop 0
	global_load_lds_dwordx4 v154, s[2:3]
	s_add_i32 m0, s18, 0x2000
	s_nop 0
	global_load_lds_dwordx4 v130, s[2:3]
	s_waitcnt vmcnt(6)
	s_barrier
	v_mfma_f32_16x16x32_bf16 v[54:57], v[206:209], v[172:175], v[54:57]
	v_mfma_f32_16x16x32_bf16 v[50:53], v[214:217], v[172:175], v[50:53]
	v_mfma_f32_16x16x32_bf16 v[38:41], v[206:209], v[182:185], v[38:41]
	v_mfma_f32_16x16x32_bf16 v[34:37], v[214:217], v[182:185], v[34:37]
	v_mfma_f32_16x16x32_bf16 v[22:25], v[206:209], v[190:193], v[22:25]
	v_mfma_f32_16x16x32_bf16 v[18:21], v[214:217], v[190:193], v[18:21]
	v_mfma_f32_16x16x32_bf16 v[6:9], v[206:209], v[198:201], v[6:9]
	v_mfma_f32_16x16x32_bf16 v[2:5], v[214:217], v[198:201], v[2:5]
	v_mfma_f32_16x16x32_bf16 v[54:57], v[210:213], v[176:179], v[54:57]
	v_mfma_f32_16x16x32_bf16 v[50:53], v[218:221], v[176:179], v[50:53]
	v_mfma_f32_16x16x32_bf16 v[38:41], v[210:213], v[186:189], v[38:41]
	v_mfma_f32_16x16x32_bf16 v[34:37], v[218:221], v[186:189], v[34:37]
	v_mfma_f32_16x16x32_bf16 v[22:25], v[210:213], v[194:197], v[22:25]
	v_mfma_f32_16x16x32_bf16 v[18:21], v[218:221], v[194:197], v[18:21]
	v_mfma_f32_16x16x32_bf16 v[6:9], v[210:213], v[202:205], v[6:9]
	v_mfma_f32_16x16x32_bf16 v[2:5], v[218:221], v[202:205], v[2:5]
	s_add_i32 vcc_hi, vcc_hi, 2
	s_add_u32 s12, s12, 0x100
	s_addc_u32 s13, s13, 0
	s_add_u32 s34, s34, 0x100
	s_addc_u32 s35, s35, 0
	s_cmp_gt_u32 vcc_hi, 13
	s_barrier
	s_cbranch_scc0 .LBB0_935
	v_lshl_add_u32 v142, s36, 8, v144
	v_ashrrev_i32_e32 v143, 31, v142
	v_lshl_or_b32 v140, s37, 8, v146
	v_lshlrev_b64 v[150:151], 11, v[142:143]
	v_ashrrev_i32_e32 v141, 31, v140
	v_lshl_add_u64 v[150:151], s[58:59], 0, v[150:151]
	v_lshl_add_u64 v[164:165], v[140:141], 1, v[150:151]
	v_and_b32_e32 v245, 3, v0
	v_bfe_u32 v246, v0, 2, 4
	v_and_b32_e32 v247, 15, v0
	v_lshl_add_u32 v248, v247, 2, 0
	v_sub_u32_e32 v246, v246, v247
	v_lshlrev_b32_e32 v246, 11, v246
	v_bfe_u32 v247, v0, 4, 2
	v_add_u32_e32 v248, v248, v247
	v_lshlrev_b32_e32 v248, 2, v248
	v_sub_u32_e32 v245, v245, v247
	v_lshl_add_u32 v246, v245, 4, v246
	v_ashrrev_i32_e32 v247, 31, v246
	v_add_co_u32_e32 v164, vcc, v164, v246
	s_nop 1
	v_addc_co_u32_e32 v165, vcc, v165, v247, vcc
	v_mov_b64_e32 v[238:239], v[164:165]
	global_load_dwordx4 v[150:153], v[164:165], off
	s_nop 0
	global_load_dwordx4 v[164:167], v[164:165], off offset:256
	v_add_co_u32_e32 v240, vcc, 0x8000, v238
	s_nop 1
	v_addc_co_u32_e32 v241, vcc, 0, v239, vcc
	global_load_dwordx4 v[182:185], v[240:241], off
	global_load_dwordx4 v[186:189], v[240:241], off offset:256
	v_add_co_u32_e32 v240, vcc, 0x10000, v238
	s_nop 1
	v_addc_co_u32_e32 v241, vcc, 0, v239, vcc
	global_load_dwordx4 v[190:193], v[240:241], off
	global_load_dwordx4 v[194:197], v[240:241], off offset:256
	v_add_co_u32_e32 v240, vcc, 0x18000, v238
	s_nop 1
	v_addc_co_u32_e32 v241, vcc, 0, v239, vcc
	global_load_dwordx4 v[198:201], v[240:241], off
	global_load_dwordx4 v[202:205], v[240:241], off offset:256
	v_add_co_u32_e32 v240, vcc, 0x40000, v238
	s_nop 1
	v_addc_co_u32_e32 v241, vcc, 0, v239, vcc
	global_load_dwordx4 v[206:209], v[240:241], off
	global_load_dwordx4 v[210:213], v[240:241], off offset:256
	v_add_co_u32_e32 v240, vcc, 0x48000, v238
	s_nop 1
	v_addc_co_u32_e32 v241, vcc, 0, v239, vcc
	global_load_dwordx4 v[214:217], v[240:241], off
	global_load_dwordx4 v[218:221], v[240:241], off offset:256
	v_add_co_u32_e32 v240, vcc, 0x50000, v238
	s_nop 1
	v_addc_co_u32_e32 v241, vcc, 0, v239, vcc
	global_load_dwordx4 v[222:225], v[240:241], off
	global_load_dwordx4 v[226:229], v[240:241], off offset:256
	v_add_co_u32_e32 v240, vcc, 0x58000, v238
	s_nop 1
	v_addc_co_u32_e32 v241, vcc, 0, v239, vcc
	global_load_dwordx4 v[230:233], v[240:241], off
	global_load_dwordx4 v[234:237], v[240:241], off offset:256
	v_lshlrev_b32_e32 v148, 1, v140
	s_waitcnt vmcnt(14)
	ds_bpermute_b32 v150, v248, v150
	ds_bpermute_b32 v151, v248, v151
	ds_bpermute_b32 v152, v248, v152
	ds_bpermute_b32 v153, v248, v153
	ds_bpermute_b32 v164, v248, v164
	ds_bpermute_b32 v165, v248, v165
	ds_bpermute_b32 v166, v248, v166
	ds_bpermute_b32 v167, v248, v167
	s_waitcnt lgkmcnt(0)
	v_lshlrev_b32_e32 v149, 16, v150
	v_lshlrev_b32_e32 v171, 16, v164
	v_and_b32_e32 v164, 0xffff0000, v164
	v_and_b32_e32 v150, 0xffff0000, v150
	v_lshlrev_b32_e32 v168, 16, v151
	v_and_b32_e32 v151, 0xffff0000, v151
	v_lshlrev_b32_e32 v173, 16, v166
	v_and_b32_e32 v166, 0xffff0000, v166
	v_lshlrev_b32_e32 v174, 16, v167
	v_and_b32_e32 v167, 0xffff0000, v167
	v_add_f32_e32 v118, v118, v171
	v_add_f32_e32 v119, v119, v164
	v_lshlrev_b32_e32 v172, 16, v165
	v_add_f32_e32 v126, v126, v149
	v_add_f32_e32 v149, v114, v173
	v_add_f32_e32 v114, v127, v150
	v_add_f32_e32 v127, v115, v166
	v_add_f32_e32 v115, v128, v168
	v_add_f32_e32 v128, v116, v174
	v_add_f32_e32 v116, v129, v151
	v_add_f32_e32 v129, v117, v167
	v_mul_f32_e32 v117, v118, v118
	v_mul_f32_e32 v150, v119, v119
	v_add_f32_e32 v120, v120, v172
	v_fmac_f32_e32 v117, v126, v126
	v_fmac_f32_e32 v150, v114, v114
	v_and_b32_e32 v165, 0xffff0000, v165
	v_add_f32_e32 v117, v117, v150
	v_mul_f32_e32 v150, v120, v120
	v_add_f32_e32 v121, v121, v165
	v_fmac_f32_e32 v150, v115, v115
	v_add_f32_e32 v117, v150, v117
	v_mul_f32_e32 v150, v121, v121
	v_lshlrev_b32_e32 v169, 16, v152
	v_fmac_f32_e32 v150, v116, v116
	v_add_f32_e32 v122, v122, v169
	v_add_f32_e32 v117, v150, v117
	v_mul_f32_e32 v150, v149, v149
	v_and_b32_e32 v152, 0xffff0000, v152
	v_fmac_f32_e32 v150, v122, v122
	v_add_f32_e32 v123, v123, v152
	v_add_f32_e32 v117, v150, v117
	v_mul_f32_e32 v150, v127, v127
	v_lshlrev_b32_e32 v170, 16, v153
	v_fmac_f32_e32 v150, v123, v123
	v_add_f32_e32 v124, v124, v170
	v_add_f32_e32 v117, v150, v117
	v_mul_f32_e32 v150, v128, v128
	v_and_b32_e32 v153, 0xffff0000, v153
	v_fmac_f32_e32 v150, v124, v124
	v_add_f32_e32 v125, v125, v153
	v_add_f32_e32 v117, v150, v117
	v_mul_f32_e32 v150, v129, v129
	v_fmac_f32_e32 v150, v125, v125
	v_lshl_add_u32 v151, v142, 11, v148
	v_cvt_pk_bf16_f32 v114, v126, v114
	v_cvt_pk_bf16_f32 v115, v115, v116
	v_add_f32_e32 v150, v150, v117
	v_cvt_pk_bf16_f32 v116, v122, v123
	v_cvt_pk_bf16_f32 v117, v124, v125
	v_and_b32_e32 v245, 3, v0
	v_bfe_u32 v246, v0, 2, 4
	v_lshl_add_u32 v247, v245, 4, v246
	v_lshlrev_b32_e32 v247, 2, v247
	v_and_b32_e32 v252, 15, v0
	v_sub_u32_e32 v246, v246, v252
	v_lshlrev_b32_e32 v246, 11, v246
	v_bfe_u32 v252, v0, 4, 2
	v_sub_u32_e32 v245, v245, v252
	v_lshl_add_u32 v246, v245, 4, v246
	v_mov_b32_e32 v245, v247
	v_add_u32_e32 v247, v246, v151
	ds_bpermute_b32 v252, v245, v114
	ds_bpermute_b32 v253, v245, v115
	ds_bpermute_b32 v254, v245, v116
	ds_bpermute_b32 v255, v245, v117
	s_nop 1
	v_cvt_pk_bf16_f32 v114, v118, v119
	v_cvt_pk_bf16_f32 v115, v120, v121
	v_cvt_pk_bf16_f32 v116, v149, v127
	v_cvt_pk_bf16_f32 v117, v128, v129
	s_waitcnt lgkmcnt(0)
	buffer_store_dwordx4 v[252:255], v247, s[64:67], 0 offen sc1
	v_add_u32_e32 v247, v246, v151
	ds_bpermute_b32 v252, v245, v114
	ds_bpermute_b32 v253, v245, v115
	ds_bpermute_b32 v254, v245, v116
	ds_bpermute_b32 v255, v245, v117
	s_nop 1
	v_and_b32_e32 v115, 64, v181
	v_xor_b32_e32 v114, 16, v181
	v_add_u32_e32 v115, 64, v115
	v_cmp_lt_i32_e32 vcc, v114, v115
	v_xor_b32_e32 v117, 32, v181
	s_nop 0
	v_cndmask_b32_e32 v114, v181, v114, vcc
	v_lshlrev_b32_e32 v116, 2, v114
	ds_bpermute_b32 v114, v116, v150
	v_cmp_lt_i32_e32 vcc, v117, v115
	s_waitcnt lgkmcnt(0)
	v_add_f32_e32 v114, v150, v114
	v_cndmask_b32_e32 v115, v181, v117, vcc
	v_lshlrev_b32_e32 v117, 2, v115
	ds_bpermute_b32 v115, v117, v114
	s_and_saveexec_b64 s[2:3], s[40:41]
	s_cbranch_execz .LBB0_938
	v_lshl_add_u64 v[118:119], v[142:143], 2, s[0:1]
	s_waitcnt lgkmcnt(0)
	v_add_f32_e32 v114, v114, v115
	global_atomic_add_f32 v[118:119], v114, off
.LBB0_938:
	s_or_b64 exec, exec, s[2:3]
	v_or_b32_e32 v114, 16, v142
	s_waitcnt lgkmcnt(0)
	v_ashrrev_i32_e32 v115, 31, v114
	v_lshlrev_b64 v[118:119], 11, v[114:115]
	v_lshl_add_u64 v[118:119], s[58:59], 0, v[118:119]
	v_lshl_add_u64 v[122:123], v[140:141], 1, v[118:119]
	s_waitcnt vmcnt(15)
	ds_bpermute_b32 v118, v248, v182
	ds_bpermute_b32 v119, v248, v183
	ds_bpermute_b32 v120, v248, v184
	ds_bpermute_b32 v121, v248, v185
	s_nop 0
	ds_bpermute_b32 v122, v248, v186
	ds_bpermute_b32 v123, v248, v187
	ds_bpermute_b32 v124, v248, v188
	ds_bpermute_b32 v125, v248, v189
	s_waitcnt lgkmcnt(0)
	v_lshlrev_b32_e32 v126, 16, v118
	v_and_b32_e32 v118, 0xffff0000, v118
	v_lshlrev_b32_e32 v143, 16, v122
	v_and_b32_e32 v122, 0xffff0000, v122
	v_lshlrev_b32_e32 v127, 16, v119
	v_lshlrev_b32_e32 v128, 16, v120
	v_lshlrev_b32_e32 v150, 16, v124
	v_lshlrev_b32_e32 v151, 16, v125
	v_add_f32_e32 v110, v110, v126
	v_add_f32_e32 v126, v102, v143
	v_add_f32_e32 v102, v111, v118
	v_add_f32_e32 v111, v103, v122
	v_lshlrev_b32_e32 v149, 16, v123
	v_add_f32_e32 v106, v106, v128
	v_add_f32_e32 v128, v98, v150
	v_add_f32_e32 v103, v112, v127
	v_add_f32_e32 v112, v100, v151
	v_mul_f32_e32 v98, v126, v126
	v_mul_f32_e32 v100, v111, v111
	v_add_f32_e32 v104, v104, v149
	v_fmac_f32_e32 v98, v110, v110
	v_fmac_f32_e32 v100, v102, v102
	v_and_b32_e32 v123, 0xffff0000, v123
	v_add_f32_e32 v98, v98, v100
	v_mul_f32_e32 v100, v104, v104
	v_and_b32_e32 v119, 0xffff0000, v119
	v_add_f32_e32 v105, v105, v123
	v_fmac_f32_e32 v100, v103, v103
	v_add_f32_e32 v113, v113, v119
	v_add_f32_e32 v98, v100, v98
	v_mul_f32_e32 v100, v105, v105
	v_fmac_f32_e32 v100, v113, v113
	v_and_b32_e32 v124, 0xffff0000, v124
	v_add_f32_e32 v98, v100, v98
	v_mul_f32_e32 v100, v128, v128
	v_and_b32_e32 v120, 0xffff0000, v120
	v_add_f32_e32 v99, v99, v124
	v_fmac_f32_e32 v100, v106, v106
	v_add_f32_e32 v107, v107, v120
	v_add_f32_e32 v98, v100, v98
	v_mul_f32_e32 v100, v99, v99
	v_lshlrev_b32_e32 v129, 16, v121
	v_fmac_f32_e32 v100, v107, v107
	v_and_b32_e32 v125, 0xffff0000, v125
	v_add_f32_e32 v108, v108, v129
	v_add_f32_e32 v98, v100, v98
	v_mul_f32_e32 v100, v112, v112
	v_and_b32_e32 v121, 0xffff0000, v121
	v_add_f32_e32 v118, v101, v125
	v_fmac_f32_e32 v100, v108, v108
	v_add_f32_e32 v109, v109, v121
	v_add_f32_e32 v98, v100, v98
	v_mul_f32_e32 v100, v118, v118
	v_fmac_f32_e32 v100, v109, v109
	v_add_f32_e32 v98, v100, v98
	v_lshl_add_u32 v119, v114, 11, v148
	v_cvt_pk_bf16_f32 v100, v110, v102
	v_cvt_pk_bf16_f32 v101, v103, v113
	v_cvt_pk_bf16_f32 v102, v106, v107
	v_cvt_pk_bf16_f32 v103, v108, v109
	s_waitcnt lgkmcnt(0)
	buffer_store_dwordx4 v[252:255], v247, s[64:67], 0 offen offset:256 sc1
	v_add_u32_e32 v247, v246, v119
	ds_bpermute_b32 v252, v245, v100
	ds_bpermute_b32 v253, v245, v101
	ds_bpermute_b32 v254, v245, v102
	ds_bpermute_b32 v255, v245, v103
	s_nop 1
	v_cvt_pk_bf16_f32 v100, v126, v111
	v_cvt_pk_bf16_f32 v101, v104, v105
	v_cvt_pk_bf16_f32 v102, v128, v99
	ds_bpermute_b32 v99, v116, v98
	v_cvt_pk_bf16_f32 v103, v112, v118
	s_waitcnt lgkmcnt(0)
	buffer_store_dwordx4 v[252:255], v247, s[64:67], 0 offen sc1
	v_add_u32_e32 v247, v246, v119
	ds_bpermute_b32 v252, v245, v100
	ds_bpermute_b32 v253, v245, v101
	ds_bpermute_b32 v254, v245, v102
	ds_bpermute_b32 v255, v245, v103
	s_waitcnt lgkmcnt(0)
	v_add_f32_e32 v98, v98, v99
	ds_bpermute_b32 v99, v117, v98
	s_and_saveexec_b64 s[2:3], s[40:41]
	s_cbranch_execz .LBB0_940
	v_lshl_add_u64 v[100:101], v[114:115], 2, s[0:1]
	s_waitcnt lgkmcnt(0)
	v_add_f32_e32 v98, v98, v99
	global_atomic_add_f32 v[100:101], v98, off
.LBB0_940:
	s_or_b64 exec, exec, s[2:3]
	v_or_b32_e32 v98, 32, v142
	s_waitcnt lgkmcnt(0)
	v_ashrrev_i32_e32 v99, 31, v98
	v_lshlrev_b64 v[100:101], 11, v[98:99]
	v_lshl_add_u64 v[100:101], s[58:59], 0, v[100:101]
	v_lshl_add_u64 v[104:105], v[140:141], 1, v[100:101]
	s_waitcnt vmcnt(16)
	ds_bpermute_b32 v100, v248, v190
	ds_bpermute_b32 v101, v248, v191
	ds_bpermute_b32 v102, v248, v192
	ds_bpermute_b32 v103, v248, v193
	s_nop 0
	ds_bpermute_b32 v104, v248, v194
	ds_bpermute_b32 v105, v248, v195
	ds_bpermute_b32 v106, v248, v196
	ds_bpermute_b32 v107, v248, v197
	s_waitcnt lgkmcnt(0)
	v_lshlrev_b32_e32 v108, 16, v100
	v_and_b32_e32 v100, 0xffff0000, v100
	v_lshlrev_b32_e32 v112, 16, v104
	v_and_b32_e32 v104, 0xffff0000, v104
	v_lshlrev_b32_e32 v109, 16, v101
	v_lshlrev_b32_e32 v110, 16, v102
	v_lshlrev_b32_e32 v114, 16, v106
	v_lshlrev_b32_e32 v115, 16, v107
	v_add_f32_e32 v94, v94, v108
	v_add_f32_e32 v108, v86, v112
	v_add_f32_e32 v86, v95, v100
	v_add_f32_e32 v95, v87, v104
	v_lshlrev_b32_e32 v113, 16, v105
	v_add_f32_e32 v90, v90, v110
	v_add_f32_e32 v110, v82, v114
	v_add_f32_e32 v87, v96, v109
	v_add_f32_e32 v96, v84, v115
	v_mul_f32_e32 v82, v108, v108
	v_mul_f32_e32 v84, v95, v95
	v_add_f32_e32 v88, v88, v113
	v_fmac_f32_e32 v82, v94, v94
	v_fmac_f32_e32 v84, v86, v86
	v_and_b32_e32 v105, 0xffff0000, v105
	v_add_f32_e32 v82, v82, v84
	v_mul_f32_e32 v84, v88, v88
	v_and_b32_e32 v101, 0xffff0000, v101
	v_add_f32_e32 v89, v89, v105
	v_fmac_f32_e32 v84, v87, v87
	v_add_f32_e32 v97, v97, v101
	v_add_f32_e32 v82, v84, v82
	v_mul_f32_e32 v84, v89, v89
	v_fmac_f32_e32 v84, v97, v97
	v_and_b32_e32 v106, 0xffff0000, v106
	v_add_f32_e32 v82, v84, v82
	v_mul_f32_e32 v84, v110, v110
	v_and_b32_e32 v102, 0xffff0000, v102
	v_add_f32_e32 v83, v83, v106
	v_fmac_f32_e32 v84, v90, v90
	v_add_f32_e32 v91, v91, v102
	v_add_f32_e32 v82, v84, v82
	v_mul_f32_e32 v84, v83, v83
	v_lshlrev_b32_e32 v111, 16, v103
	v_fmac_f32_e32 v84, v91, v91
	v_and_b32_e32 v107, 0xffff0000, v107
	v_add_f32_e32 v92, v92, v111
	v_add_f32_e32 v82, v84, v82
	v_mul_f32_e32 v84, v96, v96
	v_and_b32_e32 v103, 0xffff0000, v103
	v_add_f32_e32 v100, v85, v107
	v_fmac_f32_e32 v84, v92, v92
	v_add_f32_e32 v93, v93, v103
	v_add_f32_e32 v82, v84, v82
	v_mul_f32_e32 v84, v100, v100
	v_fmac_f32_e32 v84, v93, v93
	v_add_f32_e32 v82, v84, v82
	v_lshl_add_u32 v101, v98, 11, v148
	v_cvt_pk_bf16_f32 v84, v94, v86
	v_cvt_pk_bf16_f32 v85, v87, v97
	v_cvt_pk_bf16_f32 v86, v90, v91
	v_cvt_pk_bf16_f32 v87, v92, v93
	s_waitcnt lgkmcnt(0)
	buffer_store_dwordx4 v[252:255], v247, s[64:67], 0 offen offset:256 sc1
	v_add_u32_e32 v247, v246, v101
	ds_bpermute_b32 v252, v245, v84
	ds_bpermute_b32 v253, v245, v85
	ds_bpermute_b32 v254, v245, v86
	ds_bpermute_b32 v255, v245, v87
	s_nop 1
	v_cvt_pk_bf16_f32 v84, v108, v95
	v_cvt_pk_bf16_f32 v85, v88, v89
	v_cvt_pk_bf16_f32 v86, v110, v83
	ds_bpermute_b32 v83, v116, v82
	v_cvt_pk_bf16_f32 v87, v96, v100
	s_waitcnt lgkmcnt(0)
	buffer_store_dwordx4 v[252:255], v247, s[64:67], 0 offen sc1
	v_add_u32_e32 v247, v246, v101
	ds_bpermute_b32 v252, v245, v84
	ds_bpermute_b32 v253, v245, v85
	ds_bpermute_b32 v254, v245, v86
	ds_bpermute_b32 v255, v245, v87
	s_waitcnt lgkmcnt(0)
	v_add_f32_e32 v82, v82, v83
	ds_bpermute_b32 v83, v117, v82
	s_and_saveexec_b64 s[2:3], s[40:41]
	s_cbranch_execz .LBB0_942
	v_lshl_add_u64 v[84:85], v[98:99], 2, s[0:1]
	s_waitcnt lgkmcnt(0)
	v_add_f32_e32 v82, v82, v83
	global_atomic_add_f32 v[84:85], v82, off
.LBB0_942:
	s_or_b64 exec, exec, s[2:3]
	v_or_b32_e32 v82, 48, v142
	s_waitcnt lgkmcnt(0)
	v_ashrrev_i32_e32 v83, 31, v82
	v_lshlrev_b64 v[84:85], 11, v[82:83]
	v_lshl_add_u64 v[84:85], s[58:59], 0, v[84:85]
	v_lshl_add_u64 v[88:89], v[140:141], 1, v[84:85]
	s_waitcnt vmcnt(17)
	ds_bpermute_b32 v84, v248, v198
	ds_bpermute_b32 v85, v248, v199
	ds_bpermute_b32 v86, v248, v200
	ds_bpermute_b32 v87, v248, v201
	s_nop 0
	ds_bpermute_b32 v88, v248, v202
	ds_bpermute_b32 v89, v248, v203
	ds_bpermute_b32 v90, v248, v204
	ds_bpermute_b32 v91, v248, v205
	s_waitcnt lgkmcnt(0)
	v_lshlrev_b32_e32 v92, 16, v84
	v_and_b32_e32 v84, 0xffff0000, v84
	v_lshlrev_b32_e32 v96, 16, v88
	v_and_b32_e32 v88, 0xffff0000, v88
	v_lshlrev_b32_e32 v93, 16, v85
	v_lshlrev_b32_e32 v94, 16, v86
	v_lshlrev_b32_e32 v98, 16, v90
	v_lshlrev_b32_e32 v99, 16, v91
	v_add_f32_e32 v78, v78, v92
	v_add_f32_e32 v92, v70, v96
	v_add_f32_e32 v70, v79, v84
	v_add_f32_e32 v79, v71, v88
	v_lshlrev_b32_e32 v97, 16, v89
	v_add_f32_e32 v74, v74, v94
	v_add_f32_e32 v94, v66, v98
	v_add_f32_e32 v71, v80, v93
	v_add_f32_e32 v80, v68, v99
	v_mul_f32_e32 v66, v92, v92
	v_mul_f32_e32 v68, v79, v79
	v_add_f32_e32 v72, v72, v97
	v_fmac_f32_e32 v66, v78, v78
	v_fmac_f32_e32 v68, v70, v70
	v_and_b32_e32 v89, 0xffff0000, v89
	v_add_f32_e32 v66, v66, v68
	v_mul_f32_e32 v68, v72, v72
	v_and_b32_e32 v85, 0xffff0000, v85
	v_add_f32_e32 v73, v73, v89
	v_fmac_f32_e32 v68, v71, v71
	v_add_f32_e32 v81, v81, v85
	v_add_f32_e32 v66, v68, v66
	v_mul_f32_e32 v68, v73, v73
	v_fmac_f32_e32 v68, v81, v81
	v_and_b32_e32 v90, 0xffff0000, v90
	v_add_f32_e32 v66, v68, v66
	v_mul_f32_e32 v68, v94, v94
	v_and_b32_e32 v86, 0xffff0000, v86
	v_add_f32_e32 v67, v67, v90
	v_fmac_f32_e32 v68, v74, v74
	v_add_f32_e32 v75, v75, v86
	v_add_f32_e32 v66, v68, v66
	v_mul_f32_e32 v68, v67, v67
	v_lshlrev_b32_e32 v95, 16, v87
	v_fmac_f32_e32 v68, v75, v75
	v_and_b32_e32 v91, 0xffff0000, v91
	v_add_f32_e32 v76, v76, v95
	v_add_f32_e32 v66, v68, v66
	v_mul_f32_e32 v68, v80, v80
	v_and_b32_e32 v87, 0xffff0000, v87
	v_add_f32_e32 v84, v69, v91
	v_fmac_f32_e32 v68, v76, v76
	v_add_f32_e32 v77, v77, v87
	v_add_f32_e32 v66, v68, v66
	v_mul_f32_e32 v68, v84, v84
	v_fmac_f32_e32 v68, v77, v77
	v_add_f32_e32 v66, v68, v66
	v_lshl_add_u32 v85, v82, 11, v148
	v_cvt_pk_bf16_f32 v68, v78, v70
	v_cvt_pk_bf16_f32 v69, v71, v81
	v_cvt_pk_bf16_f32 v70, v74, v75
	v_cvt_pk_bf16_f32 v71, v76, v77
	s_waitcnt lgkmcnt(0)
	buffer_store_dwordx4 v[252:255], v247, s[64:67], 0 offen offset:256 sc1
	v_add_u32_e32 v247, v246, v85
	ds_bpermute_b32 v252, v245, v68
	ds_bpermute_b32 v253, v245, v69
	ds_bpermute_b32 v254, v245, v70
	ds_bpermute_b32 v255, v245, v71
	s_nop 1
	v_cvt_pk_bf16_f32 v68, v92, v79
	v_cvt_pk_bf16_f32 v69, v72, v73
	v_cvt_pk_bf16_f32 v70, v94, v67
	ds_bpermute_b32 v67, v116, v66
	v_cvt_pk_bf16_f32 v71, v80, v84
	s_waitcnt lgkmcnt(0)
	buffer_store_dwordx4 v[252:255], v247, s[64:67], 0 offen sc1
	v_add_u32_e32 v247, v246, v85
	ds_bpermute_b32 v252, v245, v68
	ds_bpermute_b32 v253, v245, v69
	ds_bpermute_b32 v254, v245, v70
	ds_bpermute_b32 v255, v245, v71
	s_waitcnt lgkmcnt(0)
	v_add_f32_e32 v66, v66, v67
	ds_bpermute_b32 v67, v117, v66
	s_and_saveexec_b64 s[2:3], s[40:41]
	v_readlane_b32 s24, v244, 11
	v_readlane_b32 s18, v242, 47
	v_readlane_b32 s19, v242, 48
	s_cbranch_execz .LBB0_944
	v_lshl_add_u64 v[68:69], v[82:83], 2, s[0:1]
	s_waitcnt lgkmcnt(0)
	v_add_f32_e32 v66, v66, v67
	global_atomic_add_f32 v[68:69], v66, off
.LBB0_944:
	s_or_b64 exec, exec, s[2:3]
	v_add_u32_e32 v66, 0x80, v142
	s_waitcnt lgkmcnt(0)
	v_ashrrev_i32_e32 v67, 31, v66
	v_lshlrev_b64 v[68:69], 11, v[66:67]
	v_lshl_add_u64 v[68:69], s[58:59], 0, v[68:69]
	v_lshl_add_u64 v[72:73], v[140:141], 1, v[68:69]
	s_waitcnt vmcnt(18)
	ds_bpermute_b32 v68, v248, v206
	ds_bpermute_b32 v69, v248, v207
	ds_bpermute_b32 v70, v248, v208
	ds_bpermute_b32 v71, v248, v209
	s_nop 0
	ds_bpermute_b32 v72, v248, v210
	ds_bpermute_b32 v73, v248, v211
	ds_bpermute_b32 v74, v248, v212
	ds_bpermute_b32 v75, v248, v213
	s_waitcnt lgkmcnt(0)
	v_lshlrev_b32_e32 v76, 16, v68
	v_and_b32_e32 v68, 0xffff0000, v68
	v_lshlrev_b32_e32 v80, 16, v72
	v_and_b32_e32 v72, 0xffff0000, v72
	v_lshlrev_b32_e32 v77, 16, v69
	v_lshlrev_b32_e32 v78, 16, v70
	v_lshlrev_b32_e32 v82, 16, v74
	v_lshlrev_b32_e32 v83, 16, v75
	v_add_f32_e32 v62, v62, v76
	v_add_f32_e32 v76, v54, v80
	v_add_f32_e32 v54, v63, v68
	v_add_f32_e32 v63, v55, v72
	v_lshlrev_b32_e32 v81, 16, v73
	v_add_f32_e32 v58, v58, v78
	v_add_f32_e32 v78, v50, v82
	v_add_f32_e32 v55, v64, v77
	v_add_f32_e32 v64, v52, v83
	v_mul_f32_e32 v50, v76, v76
	v_mul_f32_e32 v52, v63, v63
	v_add_f32_e32 v56, v56, v81
	v_fmac_f32_e32 v50, v62, v62
	v_fmac_f32_e32 v52, v54, v54
	v_and_b32_e32 v73, 0xffff0000, v73
	v_add_f32_e32 v50, v50, v52
	v_mul_f32_e32 v52, v56, v56
	v_and_b32_e32 v69, 0xffff0000, v69
	v_add_f32_e32 v57, v57, v73
	v_fmac_f32_e32 v52, v55, v55
	v_add_f32_e32 v65, v65, v69
	v_add_f32_e32 v50, v52, v50
	v_mul_f32_e32 v52, v57, v57
	v_fmac_f32_e32 v52, v65, v65
	v_and_b32_e32 v74, 0xffff0000, v74
	v_add_f32_e32 v50, v52, v50
	v_mul_f32_e32 v52, v78, v78
	v_and_b32_e32 v70, 0xffff0000, v70
	v_add_f32_e32 v51, v51, v74
	v_fmac_f32_e32 v52, v58, v58
	v_add_f32_e32 v59, v59, v70
	v_add_f32_e32 v50, v52, v50
	v_mul_f32_e32 v52, v51, v51
	v_lshlrev_b32_e32 v79, 16, v71
	v_fmac_f32_e32 v52, v59, v59
	v_and_b32_e32 v75, 0xffff0000, v75
	v_add_f32_e32 v60, v60, v79
	v_add_f32_e32 v50, v52, v50
	v_mul_f32_e32 v52, v64, v64
	v_and_b32_e32 v71, 0xffff0000, v71
	v_add_f32_e32 v68, v53, v75
	v_fmac_f32_e32 v52, v60, v60
	v_add_f32_e32 v61, v61, v71
	v_add_f32_e32 v50, v52, v50
	v_mul_f32_e32 v52, v68, v68
	v_fmac_f32_e32 v52, v61, v61
	v_add_f32_e32 v50, v52, v50
	v_lshl_add_u32 v69, v66, 11, v148
	v_cvt_pk_bf16_f32 v52, v62, v54
	v_cvt_pk_bf16_f32 v53, v55, v65
	v_cvt_pk_bf16_f32 v54, v58, v59
	v_cvt_pk_bf16_f32 v55, v60, v61
	s_waitcnt lgkmcnt(0)
	buffer_store_dwordx4 v[252:255], v247, s[64:67], 0 offen offset:256 sc1
	v_add_u32_e32 v247, v246, v69
	ds_bpermute_b32 v252, v245, v52
	ds_bpermute_b32 v253, v245, v53
	ds_bpermute_b32 v254, v245, v54
	ds_bpermute_b32 v255, v245, v55
	s_nop 1
	v_cvt_pk_bf16_f32 v52, v76, v63
	v_cvt_pk_bf16_f32 v53, v56, v57
	v_cvt_pk_bf16_f32 v54, v78, v51
	ds_bpermute_b32 v51, v116, v50
	v_cvt_pk_bf16_f32 v55, v64, v68
	s_waitcnt lgkmcnt(0)
	buffer_store_dwordx4 v[252:255], v247, s[64:67], 0 offen sc1
	v_add_u32_e32 v247, v246, v69
	ds_bpermute_b32 v252, v245, v52
	ds_bpermute_b32 v253, v245, v53
	ds_bpermute_b32 v254, v245, v54
	ds_bpermute_b32 v255, v245, v55
	s_waitcnt lgkmcnt(0)
	v_add_f32_e32 v50, v50, v51
	ds_bpermute_b32 v51, v117, v50
	s_and_saveexec_b64 s[2:3], s[40:41]
	s_cbranch_execz .LBB0_946
	v_lshl_add_u64 v[52:53], v[66:67], 2, s[0:1]
	s_waitcnt lgkmcnt(0)
	v_add_f32_e32 v50, v50, v51
	global_atomic_add_f32 v[52:53], v50, off
.LBB0_946:
	s_or_b64 exec, exec, s[2:3]
	v_add_u32_e32 v50, 0x90, v142
	s_waitcnt lgkmcnt(0)
	v_ashrrev_i32_e32 v51, 31, v50
	v_lshlrev_b64 v[52:53], 11, v[50:51]
	v_lshl_add_u64 v[52:53], s[58:59], 0, v[52:53]
	v_lshl_add_u64 v[56:57], v[140:141], 1, v[52:53]
	s_waitcnt vmcnt(19)
	ds_bpermute_b32 v52, v248, v214
	ds_bpermute_b32 v53, v248, v215
	ds_bpermute_b32 v54, v248, v216
	ds_bpermute_b32 v55, v248, v217
	s_nop 0
	ds_bpermute_b32 v56, v248, v218
	ds_bpermute_b32 v57, v248, v219
	ds_bpermute_b32 v58, v248, v220
	ds_bpermute_b32 v59, v248, v221
	s_waitcnt lgkmcnt(0)
	v_lshlrev_b32_e32 v60, 16, v52
	v_and_b32_e32 v52, 0xffff0000, v52
	v_lshlrev_b32_e32 v64, 16, v56
	v_and_b32_e32 v56, 0xffff0000, v56
	v_lshlrev_b32_e32 v61, 16, v53
	v_lshlrev_b32_e32 v62, 16, v54
	v_lshlrev_b32_e32 v66, 16, v58
	v_lshlrev_b32_e32 v67, 16, v59
	v_add_f32_e32 v46, v46, v60
	v_add_f32_e32 v60, v38, v64
	v_add_f32_e32 v38, v47, v52
	v_add_f32_e32 v47, v39, v56
	v_lshlrev_b32_e32 v65, 16, v57
	v_add_f32_e32 v42, v42, v62
	v_add_f32_e32 v62, v34, v66
	v_add_f32_e32 v39, v48, v61
	v_add_f32_e32 v48, v36, v67
	v_mul_f32_e32 v34, v60, v60
	v_mul_f32_e32 v36, v47, v47
	v_add_f32_e32 v40, v40, v65
	v_fmac_f32_e32 v34, v46, v46
	v_fmac_f32_e32 v36, v38, v38
	v_and_b32_e32 v57, 0xffff0000, v57
	v_add_f32_e32 v34, v34, v36
	v_mul_f32_e32 v36, v40, v40
	v_and_b32_e32 v53, 0xffff0000, v53
	v_add_f32_e32 v41, v41, v57
	v_fmac_f32_e32 v36, v39, v39
	v_add_f32_e32 v49, v49, v53
	v_add_f32_e32 v34, v36, v34
	v_mul_f32_e32 v36, v41, v41
	v_fmac_f32_e32 v36, v49, v49
	v_and_b32_e32 v58, 0xffff0000, v58
	v_add_f32_e32 v34, v36, v34
	v_mul_f32_e32 v36, v62, v62
	v_and_b32_e32 v54, 0xffff0000, v54
	v_add_f32_e32 v35, v35, v58
	v_fmac_f32_e32 v36, v42, v42
	v_add_f32_e32 v43, v43, v54
	v_add_f32_e32 v34, v36, v34
	v_mul_f32_e32 v36, v35, v35
	v_lshlrev_b32_e32 v63, 16, v55
	v_fmac_f32_e32 v36, v43, v43
	v_and_b32_e32 v59, 0xffff0000, v59
	v_add_f32_e32 v44, v44, v63
	v_add_f32_e32 v34, v36, v34
	v_mul_f32_e32 v36, v48, v48
	v_and_b32_e32 v55, 0xffff0000, v55
	v_add_f32_e32 v52, v37, v59
	v_fmac_f32_e32 v36, v44, v44
	v_add_f32_e32 v45, v45, v55
	v_add_f32_e32 v34, v36, v34
	v_mul_f32_e32 v36, v52, v52
	v_fmac_f32_e32 v36, v45, v45
	v_add_f32_e32 v34, v36, v34
	v_lshl_add_u32 v53, v50, 11, v148
	v_cvt_pk_bf16_f32 v36, v46, v38
	v_cvt_pk_bf16_f32 v37, v39, v49
	v_cvt_pk_bf16_f32 v38, v42, v43
	v_cvt_pk_bf16_f32 v39, v44, v45
	s_waitcnt lgkmcnt(0)
	buffer_store_dwordx4 v[252:255], v247, s[64:67], 0 offen offset:256 sc1
	v_add_u32_e32 v247, v246, v53
	ds_bpermute_b32 v252, v245, v36
	ds_bpermute_b32 v253, v245, v37
	ds_bpermute_b32 v254, v245, v38
	ds_bpermute_b32 v255, v245, v39
	s_nop 1
	v_cvt_pk_bf16_f32 v36, v60, v47
	v_cvt_pk_bf16_f32 v37, v40, v41
	v_cvt_pk_bf16_f32 v38, v62, v35
	ds_bpermute_b32 v35, v116, v34
	v_cvt_pk_bf16_f32 v39, v48, v52
	s_waitcnt lgkmcnt(0)
	buffer_store_dwordx4 v[252:255], v247, s[64:67], 0 offen sc1
	v_add_u32_e32 v247, v246, v53
	ds_bpermute_b32 v252, v245, v36
	ds_bpermute_b32 v253, v245, v37
	ds_bpermute_b32 v254, v245, v38
	ds_bpermute_b32 v255, v245, v39
	s_waitcnt lgkmcnt(0)
	v_add_f32_e32 v34, v34, v35
	ds_bpermute_b32 v35, v117, v34
	s_and_saveexec_b64 s[2:3], s[40:41]
	s_cbranch_execz .LBB0_948
	v_lshl_add_u64 v[36:37], v[50:51], 2, s[0:1]
	s_waitcnt lgkmcnt(0)
	v_add_f32_e32 v34, v34, v35
	global_atomic_add_f32 v[36:37], v34, off
.LBB0_948:
	s_or_b64 exec, exec, s[2:3]
	v_add_u32_e32 v34, 0xa0, v142
	s_waitcnt lgkmcnt(0)
	v_ashrrev_i32_e32 v35, 31, v34
	v_lshlrev_b64 v[36:37], 11, v[34:35]
	v_lshl_add_u64 v[36:37], s[58:59], 0, v[36:37]
	v_lshl_add_u64 v[40:41], v[140:141], 1, v[36:37]
	s_waitcnt vmcnt(20)
	ds_bpermute_b32 v36, v248, v222
	ds_bpermute_b32 v37, v248, v223
	ds_bpermute_b32 v38, v248, v224
	ds_bpermute_b32 v39, v248, v225
	s_nop 0
	ds_bpermute_b32 v40, v248, v226
	ds_bpermute_b32 v41, v248, v227
	ds_bpermute_b32 v42, v248, v228
	ds_bpermute_b32 v43, v248, v229
	s_waitcnt lgkmcnt(0)
	v_lshlrev_b32_e32 v44, 16, v36
	v_and_b32_e32 v36, 0xffff0000, v36
	v_lshlrev_b32_e32 v48, 16, v40
	v_and_b32_e32 v40, 0xffff0000, v40
	v_lshlrev_b32_e32 v45, 16, v37
	v_lshlrev_b32_e32 v46, 16, v38
	v_lshlrev_b32_e32 v50, 16, v42
	v_lshlrev_b32_e32 v51, 16, v43
	v_add_f32_e32 v30, v30, v44
	v_add_f32_e32 v44, v22, v48
	v_add_f32_e32 v22, v31, v36
	v_add_f32_e32 v31, v23, v40
	v_lshlrev_b32_e32 v49, 16, v41
	v_add_f32_e32 v26, v26, v46
	v_add_f32_e32 v46, v18, v50
	v_add_f32_e32 v23, v32, v45
	v_add_f32_e32 v32, v20, v51
	v_mul_f32_e32 v18, v44, v44
	v_mul_f32_e32 v20, v31, v31
	v_add_f32_e32 v24, v24, v49
	v_fmac_f32_e32 v18, v30, v30
	v_fmac_f32_e32 v20, v22, v22
	v_and_b32_e32 v41, 0xffff0000, v41
	v_add_f32_e32 v18, v18, v20
	v_mul_f32_e32 v20, v24, v24
	v_and_b32_e32 v37, 0xffff0000, v37
	v_add_f32_e32 v25, v25, v41
	v_fmac_f32_e32 v20, v23, v23
	v_add_f32_e32 v33, v33, v37
	v_add_f32_e32 v18, v20, v18
	v_mul_f32_e32 v20, v25, v25
	v_fmac_f32_e32 v20, v33, v33
	v_and_b32_e32 v42, 0xffff0000, v42
	v_add_f32_e32 v18, v20, v18
	v_mul_f32_e32 v20, v46, v46
	v_and_b32_e32 v38, 0xffff0000, v38
	v_add_f32_e32 v19, v19, v42
	v_fmac_f32_e32 v20, v26, v26
	v_add_f32_e32 v27, v27, v38
	v_add_f32_e32 v18, v20, v18
	v_mul_f32_e32 v20, v19, v19
	v_lshlrev_b32_e32 v47, 16, v39
	v_fmac_f32_e32 v20, v27, v27
	v_and_b32_e32 v43, 0xffff0000, v43
	v_add_f32_e32 v28, v28, v47
	v_add_f32_e32 v18, v20, v18
	v_mul_f32_e32 v20, v32, v32
	v_and_b32_e32 v39, 0xffff0000, v39
	v_add_f32_e32 v36, v21, v43
	v_fmac_f32_e32 v20, v28, v28
	v_add_f32_e32 v29, v29, v39
	v_add_f32_e32 v18, v20, v18
	v_mul_f32_e32 v20, v36, v36
	v_fmac_f32_e32 v20, v29, v29
	v_add_f32_e32 v18, v20, v18
	v_lshl_add_u32 v37, v34, 11, v148
	v_cvt_pk_bf16_f32 v20, v30, v22
	v_cvt_pk_bf16_f32 v21, v23, v33
	v_cvt_pk_bf16_f32 v22, v26, v27
	v_cvt_pk_bf16_f32 v23, v28, v29
	s_waitcnt lgkmcnt(0)
	buffer_store_dwordx4 v[252:255], v247, s[64:67], 0 offen offset:256 sc1
	v_add_u32_e32 v247, v246, v37
	ds_bpermute_b32 v252, v245, v20
	ds_bpermute_b32 v253, v245, v21
	ds_bpermute_b32 v254, v245, v22
	ds_bpermute_b32 v255, v245, v23
	s_nop 1
	v_cvt_pk_bf16_f32 v20, v44, v31
	v_cvt_pk_bf16_f32 v21, v24, v25
	v_cvt_pk_bf16_f32 v22, v46, v19
	ds_bpermute_b32 v19, v116, v18
	v_cvt_pk_bf16_f32 v23, v32, v36
	s_waitcnt lgkmcnt(0)
	buffer_store_dwordx4 v[252:255], v247, s[64:67], 0 offen sc1
	v_add_u32_e32 v247, v246, v37
	ds_bpermute_b32 v252, v245, v20
	ds_bpermute_b32 v253, v245, v21
	ds_bpermute_b32 v254, v245, v22
	ds_bpermute_b32 v255, v245, v23
	s_waitcnt lgkmcnt(0)
	v_add_f32_e32 v18, v18, v19
	ds_bpermute_b32 v19, v117, v18
	s_and_saveexec_b64 s[2:3], s[40:41]
	s_cbranch_execz .LBB0_950
	v_lshl_add_u64 v[20:21], v[34:35], 2, s[0:1]
	s_waitcnt lgkmcnt(0)
	v_add_f32_e32 v18, v18, v19
	global_atomic_add_f32 v[20:21], v18, off
.LBB0_950:
	s_or_b64 exec, exec, s[2:3]
	v_add_u32_e32 v18, 0xb0, v142
	s_waitcnt lgkmcnt(0)
	v_ashrrev_i32_e32 v19, 31, v18
	v_lshlrev_b64 v[20:21], 11, v[18:19]
	v_lshl_add_u64 v[20:21], s[58:59], 0, v[20:21]
	v_lshl_add_u64 v[24:25], v[140:141], 1, v[20:21]
	s_waitcnt vmcnt(21)
	ds_bpermute_b32 v20, v248, v230
	ds_bpermute_b32 v21, v248, v231
	ds_bpermute_b32 v22, v248, v232
	ds_bpermute_b32 v23, v248, v233
	s_nop 0
	ds_bpermute_b32 v24, v248, v234
	ds_bpermute_b32 v25, v248, v235
	ds_bpermute_b32 v26, v248, v236
	ds_bpermute_b32 v27, v248, v237
	s_waitcnt lgkmcnt(0)
	v_lshl_add_u32 v28, v18, 11, v148
	v_lshlrev_b32_e32 v29, 16, v20
	v_lshlrev_b32_e32 v33, 16, v24
	v_and_b32_e32 v24, 0xffff0000, v24
	v_and_b32_e32 v20, 0xffff0000, v20
	v_lshlrev_b32_e32 v30, 16, v21
	v_and_b32_e32 v21, 0xffff0000, v21
	v_lshlrev_b32_e32 v34, 16, v25
	v_lshlrev_b32_e32 v35, 16, v26
	v_and_b32_e32 v26, 0xffff0000, v26
	v_lshlrev_b32_e32 v36, 16, v27
	v_and_b32_e32 v27, 0xffff0000, v27
	v_add_f32_e32 v6, v6, v33
	v_add_f32_e32 v7, v7, v24
	v_lshlrev_b32_e32 v31, 16, v22
	v_and_b32_e32 v22, 0xffff0000, v22
	v_and_b32_e32 v25, 0xffff0000, v25
	v_add_f32_e32 v14, v14, v29
	v_add_f32_e32 v15, v15, v20
	v_add_f32_e32 v20, v3, v26
	v_add_f32_e32 v3, v16, v30
	v_add_f32_e32 v8, v8, v34
	v_add_f32_e32 v16, v4, v36
	v_add_f32_e32 v4, v17, v21
	v_add_f32_e32 v17, v5, v27
	v_mul_f32_e32 v5, v6, v6
	v_mul_f32_e32 v21, v7, v7
	v_lshlrev_b32_e32 v32, 16, v23
	v_and_b32_e32 v23, 0xffff0000, v23
	v_add_f32_e32 v11, v11, v22
	v_add_f32_e32 v9, v9, v25
	v_mul_f32_e32 v22, v8, v8
	v_fmac_f32_e32 v5, v14, v14
	v_fmac_f32_e32 v21, v15, v15
	v_add_f32_e32 v29, v2, v35
	v_add_f32_e32 v13, v13, v23
	v_mul_f32_e32 v23, v9, v9
	v_fmac_f32_e32 v22, v3, v3
	v_add_f32_e32 v5, v5, v21
	v_add_f32_e32 v10, v10, v31
	v_mul_f32_e32 v24, v29, v29
	v_fmac_f32_e32 v23, v4, v4
	v_add_f32_e32 v5, v22, v5
	v_mul_f32_e32 v25, v20, v20
	v_fmac_f32_e32 v24, v10, v10
	v_add_f32_e32 v5, v23, v5
	v_add_f32_e32 v12, v12, v32
	v_mul_f32_e32 v26, v16, v16
	v_fmac_f32_e32 v25, v11, v11
	v_add_f32_e32 v5, v24, v5
	v_mul_f32_e32 v27, v17, v17
	v_fmac_f32_e32 v26, v12, v12
	v_add_f32_e32 v5, v25, v5
	v_fmac_f32_e32 v27, v13, v13
	v_add_f32_e32 v5, v26, v5
	v_cvt_pk_bf16_f32 v2, v14, v15
	v_add_f32_e32 v14, v27, v5
	ds_bpermute_b32 v15, v116, v14
	v_cvt_pk_bf16_f32 v3, v3, v4
	v_cvt_pk_bf16_f32 v4, v10, v11
	v_cvt_pk_bf16_f32 v5, v12, v13
	s_waitcnt lgkmcnt(0)
	buffer_store_dwordx4 v[252:255], v247, s[64:67], 0 offen offset:256 sc1
	v_add_u32_e32 v247, v246, v28
	ds_bpermute_b32 v252, v245, v2
	ds_bpermute_b32 v253, v245, v3
	ds_bpermute_b32 v254, v245, v4
	ds_bpermute_b32 v255, v245, v5
	s_waitcnt lgkmcnt(0)
	s_nop 0
	v_add_f32_e32 v2, v14, v15
	ds_bpermute_b32 v3, v117, v2
	v_cvt_pk_bf16_f32 v4, v6, v7
	v_cvt_pk_bf16_f32 v5, v8, v9
	v_cvt_pk_bf16_f32 v6, v29, v20
	v_cvt_pk_bf16_f32 v7, v16, v17
	s_waitcnt lgkmcnt(0)
	buffer_store_dwordx4 v[252:255], v247, s[64:67], 0 offen sc1
	v_add_u32_e32 v247, v246, v28
	ds_bpermute_b32 v252, v245, v4
	ds_bpermute_b32 v253, v245, v5
	ds_bpermute_b32 v254, v245, v6
	ds_bpermute_b32 v255, v245, v7
	s_waitcnt lgkmcnt(0)
	buffer_store_dwordx4 v[252:255], v247, s[64:67], 0 offen offset:256 sc1
	s_and_saveexec_b64 s[2:3], s[40:41]
	s_cbranch_execz .LBB0_927
	v_lshl_add_u64 v[4:5], v[18:19], 2, s[0:1]
	s_waitcnt lgkmcnt(0)
	v_add_f32_e32 v2, v2, v3
	global_atomic_add_f32 v[4:5], v2, off
	s_branch .LBB0_927
